# plus: nt loads for the f32 x residual rows in the out-proj fused epilogue
# baseline (speedup 1.0000x reference)
.LBB0_228:
	s_lshl_b32 s2, s38, 5
	s_lshl_b32 s3, s18, 8
	s_or_b32 s2, s3, s2
	v_lshrrev_b32_e32 v122, 2, v210
	s_lshl_b32 s30, s29, 8
	v_and_or_b32 v214, v122, 12, s2
	s_add_i32 s2, s30, s28
	v_or_b32_e32 v122, s2, v219
	v_ashrrev_i32_e32 v215, 31, v214
	v_lshlrev_b64 v[124:125], 2, v[214:215]
	v_ashrrev_i32_e32 v123, 31, v122
	v_lshl_add_u64 v[216:217], s[0:1], 0, v[124:125]
	v_lshlrev_b64 v[130:131], 12, v[122:123]
	v_lshl_add_u64 v[130:131], v[216:217], 0, v[130:131]
	s_barrier
	global_load_dwordx4 v[206:209], v[130:131], off nt
	global_load_dwordx4 v[202:205], v[130:131], off offset:64 nt
	global_load_dwordx4 v[198:201], v[130:131], off offset:512 nt
	global_load_dwordx4 v[194:197], v[130:131], off offset:576 nt
	v_or_b32_e32 v130, 16, v122
	v_ashrrev_i32_e32 v131, 31, v130
	v_lshlrev_b64 v[130:131], 12, v[130:131]
	v_lshl_add_u64 v[130:131], v[216:217], 0, v[130:131]
	global_load_dwordx4 v[190:193], v[130:131], off nt
	global_load_dwordx4 v[186:189], v[130:131], off offset:64 nt
	global_load_dwordx4 v[182:185], v[130:131], off offset:512 nt
	global_load_dwordx4 v[178:181], v[130:131], off offset:576 nt
	v_or_b32_e32 v130, 32, v122
	v_or_b32_e32 v122, 48, v122
	v_ashrrev_i32_e32 v131, 31, v130
	v_ashrrev_i32_e32 v123, 31, v122
	v_lshlrev_b64 v[130:131], 12, v[130:131]
	v_lshlrev_b64 v[122:123], 12, v[122:123]
	v_lshl_add_u64 v[130:131], v[216:217], 0, v[130:131]
	v_lshl_add_u64 v[122:123], v[216:217], 0, v[122:123]
	global_load_dwordx4 v[174:177], v[130:131], off nt
	global_load_dwordx4 v[170:173], v[130:131], off offset:64 nt
	global_load_dwordx4 v[166:169], v[130:131], off offset:512 nt
	global_load_dwordx4 v[162:165], v[130:131], off offset:576 nt
	global_load_dwordx4 v[158:161], v[122:123], off nt
	global_load_dwordx4 v[154:157], v[122:123], off offset:64 nt
	global_load_dwordx4 v[150:153], v[122:123], off offset:512 nt
	global_load_dwordx4 v[146:149], v[122:123], off offset:576 nt
	v_lshl_add_u64 v[122:123], s[22:23], 0, v[124:125]
	global_load_dwordx4 v[142:145], v[122:123], off nt
	global_load_dwordx4 v[134:137], v[122:123], off offset:64 nt
	global_load_dwordx4 v[130:133], v[122:123], off offset:512 nt
	s_nop 0
	global_load_dwordx4 v[122:125], v[122:123], off offset:576 nt
	v_mul_f32_e32 v211, v139, v139
	v_mul_f32_e32 v212, v141, v141
	v_fmac_f32_e32 v211, v138, v138
	v_fmac_f32_e32 v212, v140, v140
	v_add_f32_e32 v211, v211, v212
	v_mul_f32_e32 v212, v127, v127
	v_mul_f32_e32 v213, v129, v129
	v_fmac_f32_e32 v212, v126, v126
	v_fmac_f32_e32 v213, v128, v128
	v_add_f32_e32 v212, v212, v213
	v_add_f32_e32 v211, v212, v211
	v_mul_f32_e32 v212, v119, v119
	v_mul_f32_e32 v213, v121, v121
	v_fmac_f32_e32 v212, v118, v118
	v_fmac_f32_e32 v213, v120, v120
	v_add_f32_e32 v212, v212, v213
	v_add_f32_e32 v211, v212, v211
	v_mul_f32_e32 v212, v115, v115
	v_mul_f32_e32 v213, v117, v117
	v_fmac_f32_e32 v212, v114, v114
	v_fmac_f32_e32 v213, v116, v116
	v_add_f32_e32 v212, v212, v213
	v_add_f32_e32 v211, v212, v211
	ds_bpermute_b32 v212, v1, v211
	v_and_b32_e32 v226, 63, v210
	s_lshl_b32 s0, s38, 2
	v_cmp_gt_u32_e64 s[4:5], 16, v226
	s_add_i32 s31, s0, 0
	s_waitcnt lgkmcnt(0)
	v_add_f32_e32 v211, v211, v212
	ds_bpermute_b32 v212, v233, v211
	s_and_saveexec_b64 s[0:1], s[4:5]
	s_cbranch_execz .LBB0_230
	s_lshl_b32 s2, s24, 10
	s_add_i32 s2, s31, s2
	v_lshl_add_u32 v213, v219, 4, s2
	s_waitcnt lgkmcnt(0)
	v_add_f32_e32 v211, v211, v212
	ds_write_b32 v213, v211

.LBB0_266:
	s_or_b64 exec, exec, s[2:3]
	s_add_i32 s2, s28, 0x80
	v_or_b32_e32 v66, s2, v219
	v_add_u32_e32 v74, s30, v66
	v_ashrrev_i32_e32 v75, 31, v74
	v_lshlrev_b64 v[68:69], 12, v[74:75]
	v_lshl_add_u64 v[76:77], v[216:217], 0, v[68:69]
	global_load_dwordx4 v[70:73], v[76:77], off nt
	s_waitcnt lgkmcnt(0)
	v_add_u32_e32 v67, s28, v219
	v_lshl_add_u32 v67, v67, 2, 0
	ds_read_b32 v78, v67 offset:8704
	v_lshlrev_b64 v[74:75], 10, v[74:75]
	v_lshl_add_u64 v[74:75], v[74:75], 0, v[214:215]
	v_mov_b32_e32 v68, 0x7fc00000
	v_lshl_add_u64 v[74:75], v[74:75], 1, s[0:1]
	s_waitcnt lgkmcnt(0)
	v_pk_mul_f32 v[64:65], v[64:65], v[78:79] op_sel_hi:[1,0]
	v_pk_mul_f32 v[62:63], v[62:63], v[78:79] op_sel_hi:[1,0]
	v_pk_mul_f32 v[60:61], v[60:61], v[78:79] op_sel_hi:[1,0]
	v_pk_mul_f32 v[58:59], v[58:59], v[78:79] op_sel_hi:[1,0]
	v_pk_mul_f32 v[56:57], v[56:57], v[78:79] op_sel_hi:[1,0]
	v_pk_mul_f32 v[54:55], v[54:55], v[78:79] op_sel_hi:[1,0]
	v_pk_mul_f32 v[52:53], v[52:53], v[78:79] op_sel_hi:[1,0]
	v_pk_mul_f32 v[50:51], v[50:51], v[78:79] op_sel_hi:[1,0]
	s_waitcnt vmcnt(0)
	v_pk_fma_f32 v[64:65], v[144:145], v[64:65], v[72:73]
	v_pk_fma_f32 v[62:63], v[142:143], v[62:63], v[70:71]
	v_cndmask_b32_e32 v69, v64, v68, vcc
	v_cndmask_b32_e32 v70, v65, v68, vcc
	v_cndmask_b32_e32 v71, v62, v68, vcc
	v_cndmask_b32_e32 v72, v63, v68, vcc
	v_cvt_pk_bf16_f32 v62, v71, v72
	v_cvt_pk_bf16_f32 v63, v69, v70
	global_store_dwordx2 v[74:75], v[62:63], off
	global_load_dwordx4 v[62:65], v[76:77], off offset:64 nt
	v_mul_f32_e32 v72, v72, v72
	v_mul_f32_e32 v70, v70, v70
	v_fmac_f32_e32 v72, v71, v71
	v_fmac_f32_e32 v70, v69, v69
	v_add_f32_e32 v69, v72, v70
	s_waitcnt vmcnt(0)
	v_pk_fma_f32 v[60:61], v[136:137], v[60:61], v[64:65]
	v_pk_fma_f32 v[58:59], v[134:135], v[58:59], v[62:63]
	v_cndmask_b32_e32 v62, v60, v68, vcc
	v_cndmask_b32_e32 v63, v61, v68, vcc
	v_cndmask_b32_e32 v64, v58, v68, vcc
	v_cndmask_b32_e32 v65, v59, v68, vcc
	v_cvt_pk_bf16_f32 v58, v64, v65
	v_cvt_pk_bf16_f32 v59, v62, v63
	global_store_dwordx2 v[74:75], v[58:59], off offset:32
	global_load_dwordx4 v[58:61], v[76:77], off offset:512 nt
	v_mul_f32_e32 v65, v65, v65
	v_mul_f32_e32 v63, v63, v63
	v_fmac_f32_e32 v65, v64, v64
	v_fmac_f32_e32 v63, v62, v62
	v_add_f32_e32 v62, v65, v63
	v_add_f32_e32 v62, v69, v62
	s_waitcnt vmcnt(0)
	v_pk_fma_f32 v[56:57], v[132:133], v[56:57], v[60:61]
	v_pk_fma_f32 v[54:55], v[130:131], v[54:55], v[58:59]
	v_cndmask_b32_e32 v58, v56, v68, vcc
	v_cndmask_b32_e32 v59, v57, v68, vcc
	v_cndmask_b32_e32 v60, v54, v68, vcc
	v_cndmask_b32_e32 v61, v55, v68, vcc
	v_cvt_pk_bf16_f32 v54, v60, v61
	v_cvt_pk_bf16_f32 v55, v58, v59
	global_store_dwordx2 v[74:75], v[54:55], off offset:256
	global_load_dwordx4 v[54:57], v[76:77], off offset:576 nt
	v_mul_f32_e32 v61, v61, v61
	v_mul_f32_e32 v59, v59, v59
	v_fmac_f32_e32 v61, v60, v60
	v_fmac_f32_e32 v59, v58, v58
	v_add_f32_e32 v58, v61, v59
	v_add_f32_e32 v58, v62, v58
	s_waitcnt vmcnt(0)
	v_pk_fma_f32 v[52:53], v[124:125], v[52:53], v[56:57]
	v_pk_fma_f32 v[50:51], v[122:123], v[50:51], v[54:55]
	v_cndmask_b32_e32 v53, v53, v68, vcc
	v_cndmask_b32_e32 v55, v51, v68, vcc
	v_cndmask_b32_e32 v54, v52, v68, vcc
	v_cndmask_b32_e32 v52, v50, v68, vcc
	v_mul_f32_e32 v50, v55, v55
	v_mul_f32_e32 v51, v53, v53
	v_fmac_f32_e32 v50, v52, v52
	v_fmac_f32_e32 v51, v54, v54
	v_add_f32_e32 v50, v50, v51
	v_add_f32_e32 v50, v58, v50
	ds_bpermute_b32 v51, v1, v50
	v_cvt_pk_bf16_f32 v52, v52, v55
	v_cvt_pk_bf16_f32 v53, v54, v53
	global_store_dwordx2 v[74:75], v[52:53], off offset:288
	s_waitcnt lgkmcnt(0)
	v_add_f32_e32 v50, v50, v51
	ds_bpermute_b32 v51, v233, v50
	s_and_saveexec_b64 s[2:3], s[4:5]
	s_cbranch_execz .LBB0_268
	v_lshl_add_u32 v52, v66, 4, s31
	s_waitcnt lgkmcnt(0)
	v_add_f32_e32 v50, v50, v51
	ds_write_b32 v52, v50 offset:16384
.LBB0_268:
	s_or_b64 exec, exec, s[2:3]
	v_or_b32_e32 v50, 16, v66
	v_add_u32_e32 v56, s30, v50
	v_ashrrev_i32_e32 v57, 31, v56
	v_lshlrev_b64 v[52:53], 12, v[56:57]
	v_lshl_add_u64 v[58:59], v[216:217], 0, v[52:53]
	global_load_dwordx4 v[52:55], v[58:59], off nt
	ds_read_b32 v60, v67 offset:8768
	v_lshlrev_b64 v[56:57], 10, v[56:57]
	v_lshl_add_u64 v[56:57], v[56:57], 0, v[214:215]
	v_lshl_add_u64 v[56:57], v[56:57], 1, s[0:1]
	s_waitcnt lgkmcnt(0)
	v_pk_mul_f32 v[48:49], v[48:49], v[60:61] op_sel_hi:[1,0]
	v_pk_mul_f32 v[46:47], v[46:47], v[60:61] op_sel_hi:[1,0]
	v_pk_mul_f32 v[44:45], v[44:45], v[60:61] op_sel_hi:[1,0]
	v_pk_mul_f32 v[42:43], v[42:43], v[60:61] op_sel_hi:[1,0]
	v_pk_mul_f32 v[40:41], v[40:41], v[60:61] op_sel_hi:[1,0]
	v_pk_mul_f32 v[38:39], v[38:39], v[60:61] op_sel_hi:[1,0]
	v_pk_mul_f32 v[36:37], v[36:37], v[60:61] op_sel_hi:[1,0]
	v_pk_mul_f32 v[34:35], v[34:35], v[60:61] op_sel_hi:[1,0]
	s_waitcnt vmcnt(0)
	v_pk_fma_f32 v[48:49], v[144:145], v[48:49], v[54:55]
	v_pk_fma_f32 v[46:47], v[142:143], v[46:47], v[52:53]
	v_cndmask_b32_e32 v51, v48, v68, vcc
	v_cndmask_b32_e32 v52, v49, v68, vcc
	v_cndmask_b32_e32 v53, v46, v68, vcc
	v_cndmask_b32_e32 v54, v47, v68, vcc
	v_cvt_pk_bf16_f32 v46, v53, v54
	v_cvt_pk_bf16_f32 v47, v51, v52
	global_store_dwordx2 v[56:57], v[46:47], off
	global_load_dwordx4 v[46:49], v[58:59], off offset:64 nt
	v_mul_f32_e32 v54, v54, v54
	v_mul_f32_e32 v52, v52, v52
	v_fmac_f32_e32 v54, v53, v53
	v_fmac_f32_e32 v52, v51, v51
	v_add_f32_e32 v51, v54, v52
	s_waitcnt vmcnt(0)
	v_pk_fma_f32 v[44:45], v[136:137], v[44:45], v[48:49]
	v_pk_fma_f32 v[42:43], v[134:135], v[42:43], v[46:47]
	v_cndmask_b32_e32 v46, v44, v68, vcc
	v_cndmask_b32_e32 v47, v45, v68, vcc
	v_cndmask_b32_e32 v48, v42, v68, vcc
	v_cndmask_b32_e32 v49, v43, v68, vcc
	v_cvt_pk_bf16_f32 v42, v48, v49
	v_cvt_pk_bf16_f32 v43, v46, v47
	global_store_dwordx2 v[56:57], v[42:43], off offset:32
	global_load_dwordx4 v[42:45], v[58:59], off offset:512 nt
	v_mul_f32_e32 v49, v49, v49
	v_mul_f32_e32 v47, v47, v47
	v_fmac_f32_e32 v49, v48, v48
	v_fmac_f32_e32 v47, v46, v46
	v_add_f32_e32 v46, v49, v47
	v_add_f32_e32 v46, v51, v46
	s_waitcnt vmcnt(0)
	v_pk_fma_f32 v[40:41], v[132:133], v[40:41], v[44:45]
	v_pk_fma_f32 v[38:39], v[130:131], v[38:39], v[42:43]
	v_cndmask_b32_e32 v42, v40, v68, vcc
	v_cndmask_b32_e32 v43, v41, v68, vcc
	v_cndmask_b32_e32 v44, v38, v68, vcc
	v_cndmask_b32_e32 v45, v39, v68, vcc
	v_cvt_pk_bf16_f32 v38, v44, v45
	v_cvt_pk_bf16_f32 v39, v42, v43
	global_store_dwordx2 v[56:57], v[38:39], off offset:256
	global_load_dwordx4 v[38:41], v[58:59], off offset:576 nt
	v_mul_f32_e32 v45, v45, v45
	v_mul_f32_e32 v43, v43, v43
	v_fmac_f32_e32 v45, v44, v44
	v_fmac_f32_e32 v43, v42, v42
	v_add_f32_e32 v42, v45, v43
	v_add_f32_e32 v42, v46, v42
	s_waitcnt vmcnt(0)
	v_pk_fma_f32 v[36:37], v[124:125], v[36:37], v[40:41]
	v_pk_fma_f32 v[34:35], v[122:123], v[34:35], v[38:39]
	v_cndmask_b32_e32 v37, v37, v68, vcc
	v_cndmask_b32_e32 v39, v35, v68, vcc
	v_cndmask_b32_e32 v38, v36, v68, vcc
	v_cndmask_b32_e32 v36, v34, v68, vcc
	v_mul_f32_e32 v34, v39, v39
	v_mul_f32_e32 v35, v37, v37
	v_fmac_f32_e32 v34, v36, v36
	v_fmac_f32_e32 v35, v38, v38
	v_add_f32_e32 v34, v34, v35
	v_add_f32_e32 v34, v42, v34
	ds_bpermute_b32 v35, v1, v34
	v_cvt_pk_bf16_f32 v36, v36, v39
	v_cvt_pk_bf16_f32 v37, v38, v37
	global_store_dwordx2 v[56:57], v[36:37], off offset:288
	s_waitcnt lgkmcnt(0)
	v_add_f32_e32 v34, v34, v35
	ds_bpermute_b32 v35, v233, v34
	s_and_saveexec_b64 s[2:3], s[4:5]
	s_cbranch_execz .LBB0_270
	v_lshl_add_u32 v36, v50, 4, s31
	s_waitcnt lgkmcnt(0)
	v_add_f32_e32 v34, v34, v35
	ds_write_b32 v36, v34 offset:16384
.LBB0_270:
	s_or_b64 exec, exec, s[2:3]
	s_waitcnt lgkmcnt(0)
	v_or_b32_e32 v35, 32, v66
	v_add_u32_e32 v40, s30, v35
	v_ashrrev_i32_e32 v41, 31, v40
	v_lshlrev_b64 v[36:37], 12, v[40:41]
	v_lshl_add_u64 v[42:43], v[216:217], 0, v[36:37]
	global_load_dwordx4 v[36:39], v[42:43], off nt
	ds_read_b32 v44, v210 offset:8832
	v_lshlrev_b64 v[40:41], 10, v[40:41]
	v_lshl_add_u64 v[40:41], v[40:41], 0, v[214:215]
	v_mov_b32_e32 v34, 0x7fc00000
	v_lshl_add_u64 v[40:41], v[40:41], 1, s[0:1]
	s_waitcnt lgkmcnt(0)
	v_pk_mul_f32 v[32:33], v[32:33], v[44:45] op_sel_hi:[1,0]
	v_pk_mul_f32 v[30:31], v[30:31], v[44:45] op_sel_hi:[1,0]
	v_pk_mul_f32 v[28:29], v[28:29], v[44:45] op_sel_hi:[1,0]
	v_pk_mul_f32 v[26:27], v[26:27], v[44:45] op_sel_hi:[1,0]
	v_pk_mul_f32 v[24:25], v[24:25], v[44:45] op_sel_hi:[1,0]
	v_pk_mul_f32 v[22:23], v[22:23], v[44:45] op_sel_hi:[1,0]
	v_pk_mul_f32 v[20:21], v[20:21], v[44:45] op_sel_hi:[1,0]
	v_pk_mul_f32 v[18:19], v[18:19], v[44:45] op_sel_hi:[1,0]
	s_waitcnt vmcnt(0)
	v_pk_fma_f32 v[32:33], v[144:145], v[32:33], v[38:39]
	v_pk_fma_f32 v[30:31], v[142:143], v[30:31], v[36:37]
	v_cndmask_b32_e32 v36, v32, v34, vcc
	v_cndmask_b32_e32 v37, v33, v34, vcc
	v_cndmask_b32_e32 v38, v30, v34, vcc
	v_cndmask_b32_e32 v39, v31, v34, vcc
	v_cvt_pk_bf16_f32 v30, v38, v39
	v_cvt_pk_bf16_f32 v31, v36, v37
	global_store_dwordx2 v[40:41], v[30:31], off
	global_load_dwordx4 v[30:33], v[42:43], off offset:64 nt
	v_mul_f32_e32 v39, v39, v39
	v_mul_f32_e32 v37, v37, v37
	v_fmac_f32_e32 v39, v38, v38
	v_fmac_f32_e32 v37, v36, v36
	v_add_f32_e32 v36, v39, v37
	s_waitcnt vmcnt(0)
	v_pk_fma_f32 v[28:29], v[136:137], v[28:29], v[32:33]
	v_pk_fma_f32 v[26:27], v[134:135], v[26:27], v[30:31]
	v_cndmask_b32_e32 v30, v28, v34, vcc
	v_cndmask_b32_e32 v31, v29, v34, vcc
	v_cndmask_b32_e32 v32, v26, v34, vcc
	v_cndmask_b32_e32 v33, v27, v34, vcc
	v_cvt_pk_bf16_f32 v26, v32, v33
	v_cvt_pk_bf16_f32 v27, v30, v31
	global_store_dwordx2 v[40:41], v[26:27], off offset:32
	global_load_dwordx4 v[26:29], v[42:43], off offset:512 nt
	v_mul_f32_e32 v33, v33, v33
	v_mul_f32_e32 v31, v31, v31
	v_fmac_f32_e32 v33, v32, v32
	v_fmac_f32_e32 v31, v30, v30
	v_add_f32_e32 v30, v33, v31
	v_add_f32_e32 v30, v36, v30
	s_waitcnt vmcnt(0)
	v_pk_fma_f32 v[24:25], v[132:133], v[24:25], v[28:29]
	v_pk_fma_f32 v[22:23], v[130:131], v[22:23], v[26:27]
	v_cndmask_b32_e32 v26, v24, v34, vcc
	v_cndmask_b32_e32 v27, v25, v34, vcc
	v_cndmask_b32_e32 v28, v22, v34, vcc
	v_cndmask_b32_e32 v29, v23, v34, vcc
	v_cvt_pk_bf16_f32 v22, v28, v29
	v_cvt_pk_bf16_f32 v23, v26, v27
	global_store_dwordx2 v[40:41], v[22:23], off offset:256
	global_load_dwordx4 v[22:25], v[42:43], off offset:576 nt
	v_mul_f32_e32 v29, v29, v29
	v_mul_f32_e32 v27, v27, v27
	v_fmac_f32_e32 v29, v28, v28
	v_fmac_f32_e32 v27, v26, v26
	v_add_f32_e32 v26, v29, v27
	v_add_f32_e32 v26, v30, v26
	s_waitcnt vmcnt(0)
	v_pk_fma_f32 v[20:21], v[124:125], v[20:21], v[24:25]
	v_pk_fma_f32 v[18:19], v[122:123], v[18:19], v[22:23]
	v_cndmask_b32_e32 v21, v21, v34, vcc
	v_cndmask_b32_e32 v23, v19, v34, vcc
	v_cndmask_b32_e32 v22, v20, v34, vcc
	v_cndmask_b32_e32 v20, v18, v34, vcc
	v_mul_f32_e32 v18, v23, v23
	v_mul_f32_e32 v19, v21, v21
	v_fmac_f32_e32 v18, v20, v20
	v_fmac_f32_e32 v19, v22, v22
	v_add_f32_e32 v18, v18, v19
	v_add_f32_e32 v18, v26, v18
	ds_bpermute_b32 v19, v1, v18
	v_cvt_pk_bf16_f32 v20, v20, v23
	v_cvt_pk_bf16_f32 v21, v22, v21
	global_store_dwordx2 v[40:41], v[20:21], off offset:288
	s_waitcnt lgkmcnt(0)
	v_add_f32_e32 v18, v18, v19
	ds_bpermute_b32 v19, v233, v18
	s_and_saveexec_b64 s[2:3], s[4:5]
	s_cbranch_execz .LBB0_272
	v_lshl_add_u32 v20, v35, 4, s31
	s_waitcnt lgkmcnt(0)
	v_add_f32_e32 v18, v18, v19
	ds_write_b32 v20, v18 offset:16384
.LBB0_272:
	s_or_b64 exec, exec, s[2:3]
	v_or_b32_e32 v18, 48, v66
	v_add_u32_e32 v24, s30, v18
	v_ashrrev_i32_e32 v25, 31, v24
	v_lshlrev_b64 v[20:21], 12, v[24:25]
	v_lshl_add_u64 v[26:27], v[216:217], 0, v[20:21]
	global_load_dwordx4 v[20:23], v[26:27], off nt
	ds_read_b32 v28, v67 offset:8896
	v_lshlrev_b64 v[24:25], 10, v[24:25]
	v_lshl_add_u64 v[24:25], v[24:25], 0, v[214:215]
	v_lshl_add_u64 v[24:25], v[24:25], 1, s[0:1]
	s_waitcnt lgkmcnt(0)
	v_pk_mul_f32 v[16:17], v[16:17], v[28:29] op_sel_hi:[1,0]
	v_pk_mul_f32 v[14:15], v[14:15], v[28:29] op_sel_hi:[1,0]
	v_pk_mul_f32 v[12:13], v[12:13], v[28:29] op_sel_hi:[1,0]
	v_pk_mul_f32 v[10:11], v[10:11], v[28:29] op_sel_hi:[1,0]
	v_pk_mul_f32 v[8:9], v[8:9], v[28:29] op_sel_hi:[1,0]
	v_pk_mul_f32 v[6:7], v[6:7], v[28:29] op_sel_hi:[1,0]
	v_pk_mul_f32 v[4:5], v[4:5], v[28:29] op_sel_hi:[1,0]
	v_pk_mul_f32 v[2:3], v[2:3], v[28:29] op_sel_hi:[1,0]
	s_waitcnt vmcnt(0)
	v_pk_fma_f32 v[16:17], v[144:145], v[16:17], v[22:23]
	v_pk_fma_f32 v[14:15], v[142:143], v[14:15], v[20:21]
	v_cndmask_b32_e32 v19, v16, v34, vcc
	v_cndmask_b32_e32 v20, v17, v34, vcc
	v_cndmask_b32_e32 v21, v14, v34, vcc
	v_cndmask_b32_e32 v22, v15, v34, vcc
	v_cvt_pk_bf16_f32 v14, v21, v22
	v_cvt_pk_bf16_f32 v15, v19, v20
	global_store_dwordx2 v[24:25], v[14:15], off
	global_load_dwordx4 v[14:17], v[26:27], off offset:64 nt
	v_mul_f32_e32 v22, v22, v22
	v_mul_f32_e32 v20, v20, v20
	v_fmac_f32_e32 v22, v21, v21
	v_fmac_f32_e32 v20, v19, v19
	v_add_f32_e32 v19, v22, v20
	s_waitcnt vmcnt(0)
	v_pk_fma_f32 v[12:13], v[136:137], v[12:13], v[16:17]
	v_pk_fma_f32 v[10:11], v[134:135], v[10:11], v[14:15]
	v_cndmask_b32_e32 v14, v12, v34, vcc
	v_cndmask_b32_e32 v15, v13, v34, vcc
	v_cndmask_b32_e32 v16, v10, v34, vcc
	v_cndmask_b32_e32 v17, v11, v34, vcc
	v_cvt_pk_bf16_f32 v10, v16, v17
	v_cvt_pk_bf16_f32 v11, v14, v15
	global_store_dwordx2 v[24:25], v[10:11], off offset:32
	global_load_dwordx4 v[10:13], v[26:27], off offset:512 nt
	v_mul_f32_e32 v17, v17, v17
	v_mul_f32_e32 v15, v15, v15
	v_fmac_f32_e32 v17, v16, v16
	v_fmac_f32_e32 v15, v14, v14
	v_add_f32_e32 v14, v17, v15
	v_add_f32_e32 v14, v19, v14
	s_waitcnt vmcnt(0)
	v_pk_fma_f32 v[8:9], v[132:133], v[8:9], v[12:13]
	v_pk_fma_f32 v[6:7], v[130:131], v[6:7], v[10:11]
	v_cndmask_b32_e32 v10, v8, v34, vcc
	v_cndmask_b32_e32 v11, v9, v34, vcc
	v_cndmask_b32_e32 v12, v6, v34, vcc
	v_cndmask_b32_e32 v13, v7, v34, vcc
	v_cvt_pk_bf16_f32 v6, v12, v13
	v_cvt_pk_bf16_f32 v7, v10, v11
	global_store_dwordx2 v[24:25], v[6:7], off offset:256
	global_load_dwordx4 v[6:9], v[26:27], off offset:576 nt
	v_mul_f32_e32 v13, v13, v13
	v_mul_f32_e32 v11, v11, v11
	v_fmac_f32_e32 v13, v12, v12
	v_fmac_f32_e32 v11, v10, v10
	v_add_f32_e32 v10, v13, v11
	v_add_f32_e32 v10, v14, v10
	s_waitcnt vmcnt(0)
	v_pk_fma_f32 v[4:5], v[124:125], v[4:5], v[8:9]
	v_pk_fma_f32 v[2:3], v[122:123], v[2:3], v[6:7]
	v_cndmask_b32_e32 v5, v5, v34, vcc
	v_cndmask_b32_e32 v7, v3, v34, vcc
	v_cndmask_b32_e32 v6, v4, v34, vcc
	v_cndmask_b32_e32 v4, v2, v34, vcc
	v_mul_f32_e32 v2, v7, v7
	v_mul_f32_e32 v3, v5, v5
	v_fmac_f32_e32 v2, v4, v4
	v_fmac_f32_e32 v3, v6, v6
	v_add_f32_e32 v2, v2, v3
	v_add_f32_e32 v2, v10, v2
	ds_bpermute_b32 v3, v1, v2
	v_cvt_pk_bf16_f32 v4, v4, v7
	v_cvt_pk_bf16_f32 v5, v6, v5
	global_store_dwordx2 v[24:25], v[4:5], off offset:288
	s_waitcnt lgkmcnt(0)
	v_add_f32_e32 v2, v2, v3
	ds_bpermute_b32 v3, v233, v2
	s_and_saveexec_b64 s[0:1], s[4:5]
	s_cbranch_execz .LBB0_274
	v_lshl_add_u32 v4, v18, 4, s31
	s_waitcnt lgkmcnt(0)
	v_add_f32_e32 v2, v2, v3
	ds_write_b32 v4, v2 offset:16384
